# ret_scan: hoisted all LDS reads of the out/state MFMA section and of the post-barrier row totals (fresh registers, counted waits)
# speedup vs baseline: 1.0301x; 1.0026x over previous
.LBB0_190:
	v_lshl_add_u32 v81, v83, 2, v147
	s_waitcnt lgkmcnt(0)
	s_barrier
	ds_read_b128 v[170:173], v81
	ds_read_b128 v[174:177], v81 offset:256
	ds_read_b128 v[178:181], v81 offset:512
	ds_read_b128 v[182:185], v81 offset:768
	ds_read_b128 v[186:189], v81 offset:1024
	ds_read_b128 v[190:193], v81 offset:1280
	ds_read_b128 v[194:197], v81 offset:1536
	ds_read_b128 v[198:201], v81 offset:1792
	ds_read_b128 v[212:215], v81 offset:64
	ds_read_b128 v[216:219], v81 offset:320
	ds_read_b128 v[220:223], v81 offset:576
	ds_read_b128 v[224:227], v81 offset:832
	ds_read_b128 v[228:231], v81 offset:1088
	ds_read_b128 v[232:235], v81 offset:1344
	ds_read_b128 v[236:239], v81 offset:1600
	ds_read_b128 v[240:243], v81 offset:1856
	s_mov_b32 s4, 0xa180000
	v_lshl_add_u64 v[88:89], v[88:89], 0, s[82:83]
	v_lshl_add_u64 v[86:87], v[86:87], 0, s[82:83]
	v_lshl_add_u64 v[90:91], v[90:91], 0, s[82:83]
	s_waitcnt lgkmcnt(14)
	v_pk_add_f32 v[72:73], v[172:173], v[176:177]
	s_waitcnt lgkmcnt(14)
	v_pk_add_f32 v[70:71], v[170:171], v[174:175]
	v_lshl_add_u64 v[92:93], v[92:93], 0, s[74:75]
	s_mov_b32 s22, s23
	s_waitcnt lgkmcnt(13)
	v_pk_add_f32 v[72:73], v[72:73], v[180:181]
	s_waitcnt lgkmcnt(13)
	v_pk_add_f32 v[70:71], v[70:71], v[178:179]
	s_waitcnt lgkmcnt(12)
	v_pk_add_f32 v[72:73], v[72:73], v[184:185]
	s_waitcnt lgkmcnt(12)
	v_pk_add_f32 v[70:71], v[70:71], v[182:183]
	s_waitcnt lgkmcnt(11)
	v_pk_add_f32 v[72:73], v[72:73], v[188:189]
	s_waitcnt lgkmcnt(11)
	v_pk_add_f32 v[70:71], v[70:71], v[186:187]
	s_waitcnt lgkmcnt(10)
	v_pk_add_f32 v[72:73], v[72:73], v[192:193]
	s_waitcnt lgkmcnt(10)
	v_pk_add_f32 v[70:71], v[70:71], v[190:191]
	s_waitcnt lgkmcnt(9)
	v_pk_add_f32 v[72:73], v[72:73], v[196:197]
	s_waitcnt lgkmcnt(9)
	v_pk_add_f32 v[70:71], v[70:71], v[194:195]
	s_waitcnt lgkmcnt(8)
	v_pk_add_f32 v[66:67], v[70:71], v[198:199]
	s_nop 0
	v_fmamk_f32 v66, v66, 0x3c000000, v169
	v_cmp_gt_f32_e32 vcc, s57, v66
	v_mul_f32_e32 v70, 0x4b800000, v66
	s_waitcnt lgkmcnt(8)
	v_pk_add_f32 v[68:69], v[72:73], v[200:201]
	v_cndmask_b32_e32 v66, v66, v70, vcc
	v_rsq_f32_e32 v66, v66
	s_nop 0
	v_mul_f32_e32 v70, 0x45800000, v66
	v_cndmask_b32_e32 v66, v66, v70, vcc
	v_mul_f32_e32 v62, v62, v66
	v_lshlrev_b32_e32 v66, 2, v121
	v_mul_lo_u32 v70, v120, s62
	v_add3_u32 v70, v115, v66, v70
	v_fmamk_f32 v66, v67, 0x3c000000, v169
	v_cmp_gt_f32_e32 vcc, s57, v66
	v_mul_f32_e32 v67, 0x4b800000, v66
	s_nop 0
	v_cndmask_b32_e32 v66, v66, v67, vcc
	v_rsq_f32_e32 v66, v66
	s_nop 0
	v_mul_f32_e32 v67, 0x45800000, v66
	v_cndmask_b32_e32 v66, v66, v67, vcc
	v_mul_f32_e32 v63, v63, v66
	v_add_u32_e32 v66, 0x4200, v70
	ds_write2_b32 v66, v62, v63 offset1:132
	v_fmamk_f32 v62, v68, 0x3c000000, v169
	v_cmp_gt_f32_e32 vcc, s57, v62
	v_mul_f32_e32 v63, 0x4b800000, v62
	s_nop 0
	v_cndmask_b32_e32 v62, v62, v63, vcc
	v_rsq_f32_e32 v62, v62
	s_nop 0
	v_mul_f32_e32 v63, 0x45800000, v62
	v_cndmask_b32_e32 v62, v62, v63, vcc
	v_fmamk_f32 v63, v69, 0x3c000000, v169
	v_mul_f32_e32 v62, v64, v62
	v_cmp_gt_f32_e32 vcc, s57, v63
	v_mul_f32_e32 v64, 0x4b800000, v63
	s_nop 0
	v_cndmask_b32_e32 v63, v63, v64, vcc
	v_rsq_f32_e32 v63, v63
	s_nop 0
	v_mul_f32_e32 v64, 0x45800000, v63
	v_cndmask_b32_e32 v63, v63, v64, vcc
	v_mul_f32_e32 v63, v65, v63
	v_add_u32_e32 v64, 0x4600, v70
	ds_write2_b32 v64, v62, v63 offset0:8 offset1:140
	s_waitcnt lgkmcnt(8)
	v_pk_add_f32 v[68:69], v[214:215], v[218:219]
	s_waitcnt lgkmcnt(8)
	v_pk_add_f32 v[66:67], v[212:213], v[216:217]
	s_waitcnt lgkmcnt(7)
	v_pk_add_f32 v[68:69], v[68:69], v[222:223]
	s_waitcnt lgkmcnt(7)
	v_pk_add_f32 v[66:67], v[66:67], v[220:221]
	s_waitcnt lgkmcnt(6)
	v_pk_add_f32 v[68:69], v[68:69], v[226:227]
	s_waitcnt lgkmcnt(6)
	v_pk_add_f32 v[66:67], v[66:67], v[224:225]
	s_waitcnt lgkmcnt(5)
	v_pk_add_f32 v[68:69], v[68:69], v[230:231]
	s_waitcnt lgkmcnt(5)
	v_pk_add_f32 v[66:67], v[66:67], v[228:229]
	s_waitcnt lgkmcnt(4)
	v_pk_add_f32 v[68:69], v[68:69], v[234:235]
	s_waitcnt lgkmcnt(4)
	v_pk_add_f32 v[66:67], v[66:67], v[232:233]
	s_waitcnt lgkmcnt(3)
	v_pk_add_f32 v[68:69], v[68:69], v[238:239]
	s_waitcnt lgkmcnt(3)
	v_pk_add_f32 v[66:67], v[66:67], v[236:237]
	s_waitcnt lgkmcnt(2)
	v_pk_add_f32 v[62:63], v[66:67], v[240:241]
	s_nop 0
	v_fmamk_f32 v62, v62, 0x3c000000, v169
	v_cmp_gt_f32_e32 vcc, s57, v62
	v_mul_f32_e32 v66, 0x4b800000, v62
	s_waitcnt lgkmcnt(2)
	v_pk_add_f32 v[64:65], v[68:69], v[242:243]
	v_cndmask_b32_e32 v62, v62, v66, vcc
	v_rsq_f32_e32 v62, v62
	s_waitcnt vmcnt(0)
	v_and_b32_e32 v67, 0xffff0000, v46
	v_mul_f32_e32 v66, 0x45800000, v62
	v_cndmask_b32_e32 v62, v62, v66, vcc
	v_mul_f32_e32 v58, v58, v62
	v_fmamk_f32 v62, v63, 0x3c000000, v169
	v_cmp_gt_f32_e32 vcc, s57, v62
	v_mul_f32_e32 v63, 0x4b800000, v62
	v_lshlrev_b32_e32 v66, 16, v46
	v_cndmask_b32_e32 v62, v62, v63, vcc
	v_rsq_f32_e32 v62, v62
	s_nop 0
	v_mul_f32_e32 v63, 0x45800000, v62
	v_cndmask_b32_e32 v62, v62, v63, vcc
	v_mul_f32_e32 v59, v59, v62
	v_add_u32_e32 v62, 0x6200, v70
	ds_write2_b32 v62, v58, v59 offset0:64 offset1:196
	v_fmamk_f32 v58, v64, 0x3c000000, v169
	v_cmp_gt_f32_e32 vcc, s57, v58
	v_mul_f32_e32 v59, 0x4b800000, v58
	s_nop 0
	v_cndmask_b32_e32 v58, v58, v59, vcc
	v_rsq_f32_e32 v58, v58
	s_nop 0
	v_mul_f32_e32 v59, 0x45800000, v58
	v_cndmask_b32_e32 v58, v58, v59, vcc
	v_fmamk_f32 v59, v65, 0x3c000000, v169
	v_mul_f32_e32 v58, v60, v58
	v_cmp_gt_f32_e32 vcc, s57, v59
	v_mul_f32_e32 v60, 0x4b800000, v59
	s_nop 0
	v_cndmask_b32_e32 v59, v59, v60, vcc
	v_rsq_f32_e32 v59, v59
	s_nop 0
	v_mul_f32_e32 v60, 0x45800000, v59
	v_cndmask_b32_e32 v59, v59, v60, vcc
	v_mul_f32_e32 v59, v61, v59
	v_add_u32_e32 v60, 0x6600, v70
	ds_write2_b32 v60, v58, v59 offset0:72 offset1:204
	ds_read_b128 v[58:61], v113
	ds_read_b128 v[62:65], v113 offset:16
	s_waitcnt lgkmcnt(1)
	v_pk_mul_f32 v[58:59], v[58:59], v[66:67]
	s_nop 0
	v_cvt_pk_bf16_f32 v46, v58, v59
	v_lshlrev_b32_e32 v58, 16, v47
	v_and_b32_e32 v59, 0xffff0000, v47
	v_pk_mul_f32 v[58:59], v[60:61], v[58:59]
	s_nop 0
	v_cvt_pk_bf16_f32 v47, v58, v59
	v_lshlrev_b32_e32 v58, 16, v48
	v_and_b32_e32 v59, 0xffff0000, v48
	s_waitcnt lgkmcnt(0)
	v_pk_mul_f32 v[58:59], v[62:63], v[58:59]
	s_nop 0
	v_cvt_pk_bf16_f32 v48, v58, v59
	v_lshlrev_b32_e32 v58, 16, v49
	v_and_b32_e32 v59, 0xffff0000, v49
	v_pk_mul_f32 v[58:59], v[64:65], v[58:59]
	s_nop 0
	v_cvt_pk_bf16_f32 v49, v58, v59
	v_add_co_u32_e32 v58, vcc, s4, v96
	s_nop 1
	v_addc_co_u32_e32 v59, vcc, 0, v97, vcc
	s_andn2_b64 vcc, exec, s[48:49]
	global_store_dwordx4 v[58:59], v[46:49], off
	s_cbranch_vccz .LBB0_271

.LBB0_199:
	s_or_b64 exec, exec, s[48:49]
	s_mul_i32 s4, s22, 0xab
	s_bfe_u32 s4, s4, 0x70009
	s_mul_i32 s4, s4, 3
	s_sub_i32 s4, s22, s4
	v_cvt_pk_bf16_f32 v58, v58, v59
	v_cvt_pk_bf16_f32 v59, v60, v61
	s_and_b32 s4, s4, 0xff
	ds_write_b64 v116, v[58:59]
	v_ashrrev_i32_e32 v58, 2, v97
	v_lshlrev_b32_e32 v83, 2, v96
	s_mul_i32 s4, s4, 0x8c00
	v_add_u32_e32 v119, v58, v83
	v_lshlrev_b32_e32 v58, 3, v97
	v_add_u32_e32 v62, s4, v168
	v_and_b32_e32 v58, 24, v58
	v_mul_lo_u32 v59, v119, s65
	v_add_u32_e32 v132, v62, v58
	v_add3_u32 v58, v132, v118, v59
	v_lshl_add_u32 v134, v96, 3, v62
	v_add_u32_e32 v62, v144, v108
	ds_read_b64_tr_b16 v[136:137], v58 offset:18432
	ds_read_b64_tr_b16 v[138:139], v58 offset:22784
	ds_read_b64_tr_b16 v[152:153], v58 offset:27136
	ds_read_b64_tr_b16 v[154:155], v58 offset:31488
	ds_read_b128 v[156:159], v62
	v_add_u32_e32 v140, s45, v97
	v_mad_u64_u32 v[160:161], s[4:5], v140, s56, v[134:135]
	ds_read2_b64 v[170:173], v160 offset1:4
	ds_read2_b64 v[174:177], v160 offset0:8 offset1:12
	v_add_u32_e32 v141, v144, v114
	ds_read_b128 v[178:181], v141 offset:1024
	ds_read_b128 v[182:185], v141
	v_add_u32_e32 v142, s43, v97
	v_mad_u64_u32 v[162:163], s[4:5], v142, s56, v[134:135]
	ds_read2_b64 v[186:189], v162 offset1:4
	ds_read2_b64 v[190:193], v162 offset0:8 offset1:12
	v_mad_u64_u32 v[194:195], s[4:5], v119, s56, v[132:133]
	ds_read_b64_tr_b16 v[196:197], v194 offset:9216
	ds_read_b64_tr_b16 v[200:201], v194 offset:9248
	ds_read_b64_tr_b16 v[198:199], v194 offset:11520
	ds_read_b64_tr_b16 v[212:213], v194 offset:13824
	ds_read_b64_tr_b16 v[214:215], v194 offset:16128
	ds_read_b64_tr_b16 v[202:203], v194 offset:11552
	ds_read_b64_tr_b16 v[216:217], v194 offset:13856
	ds_read_b64_tr_b16 v[218:219], v194 offset:16160
	ds_read_b64_tr_b16 v[220:221], v194 offset:9280
	ds_read_b64_tr_b16 v[222:223], v194 offset:11584
	ds_read_b64_tr_b16 v[224:225], v194 offset:13888
	ds_read_b64_tr_b16 v[226:227], v194 offset:16192
	ds_read_b64_tr_b16 v[228:229], v194 offset:9312
	ds_read_b64_tr_b16 v[230:231], v194 offset:11616
	ds_read_b64_tr_b16 v[232:233], v194 offset:13920
	ds_read_b64_tr_b16 v[234:235], v194 offset:16224
	s_waitcnt lgkmcnt(15)
	v_mfma_f32_16x16x32_bf16 v[62:65], v[156:159], v[136:139], v[0:3]
	v_cvt_pk_bf16_f32 v58, v50, v51
	v_cvt_pk_bf16_f32 v59, v52, v53
	v_cvt_pk_bf16_f32 v60, v38, v39
	v_cvt_pk_bf16_f32 v61, v40, v41
	v_cvt_pk_bf16_f32 v120, v42, v43
	v_cvt_pk_bf16_f32 v121, v44, v45
	s_waitcnt lgkmcnt(15)
	v_mfma_f32_16x16x32_bf16 v[62:65], v[170:173], v[58:61], v[62:65]
	v_cvt_pk_bf16_f32 v122, v54, v55
	v_cvt_pk_bf16_f32 v123, v56, v57
	s_waitcnt lgkmcnt(15)
	s_nop 1
	v_mfma_f32_16x16x32_bf16 v[62:65], v[174:177], v[120:123], v[62:65]
	s_waitcnt lgkmcnt(15)
	v_mfma_f32_16x16x32_bf16 v[124:127], v[182:185], v[136:139], v[0:3]
	v_mov_b32_e32 v81, v80
	v_pk_mul_f32 v[52:53], v[80:81], v[52:53]
	v_pk_mul_f32 v[50:51], v[84:85], v[50:51]
	s_waitcnt lgkmcnt(15)
	v_mfma_f32_16x16x32_bf16 v[124:127], v[178:181], v[152:155], v[124:127]
	v_pk_mul_f32 v[40:41], v[80:81], v[40:41]
	v_pk_mul_f32 v[38:39], v[84:85], v[38:39]
	s_waitcnt lgkmcnt(15)
	v_mfma_f32_16x16x32_bf16 v[58:61], v[186:189], v[58:61], v[124:127]
	s_nop 2
	s_waitcnt lgkmcnt(15)
	v_mfma_f32_16x16x32_bf16 v[58:61], v[190:193], v[120:123], v[58:61]
	v_pk_mul_f32 v[44:45], v[80:81], v[44:45]
	v_pk_mul_f32 v[42:43], v[84:85], v[42:43]
	s_waitcnt lgkmcnt(13)
	v_mfma_f32_16x16x32_bf16 v[50:53], v[196:199], v[136:139], v[50:53]
	v_pk_mul_f32 v[56:57], v[80:81], v[56:57]
	s_waitcnt lgkmcnt(11)
	v_mfma_f32_16x16x32_bf16 v[50:53], v[212:215], v[152:155], v[50:53]
	v_pk_mul_f32 v[54:55], v[84:85], v[54:55]
	v_cmp_eq_u32_e32 vcc, 0, v97
	s_waitcnt lgkmcnt(10)
	v_mfma_f32_16x16x32_bf16 v[38:41], v[200:203], v[136:139], v[38:41]
	s_waitcnt lgkmcnt(8)
	v_mfma_f32_16x16x32_bf16 v[38:41], v[216:219], v[152:155], v[38:41]
	s_waitcnt lgkmcnt(6)
	v_mfma_f32_16x16x32_bf16 v[42:45], v[220:223], v[136:139], v[42:45]
	s_waitcnt lgkmcnt(4)
	v_mfma_f32_16x16x32_bf16 v[42:45], v[224:227], v[152:155], v[42:45]
	s_waitcnt lgkmcnt(2)
	v_mfma_f32_16x16x32_bf16 v[54:57], v[228:231], v[136:139], v[54:57]
	s_waitcnt lgkmcnt(0)
	v_mfma_f32_16x16x32_bf16 v[54:57], v[232:235], v[152:155], v[54:57]
	v_mul_f32_e32 v67, v62, v62
	v_mov_b32_e32 v68, v165
	v_add_u32_e32 v66, v83, v112
	v_lshl_add_u32 v66, v66, 2, v143
	v_mov_b32_dpp v68, v67 quad_perm:[1,0,3,2] row_mask:0xf bank_mask:0xf
	v_fmac_f32_e32 v68, v62, v62
	s_nop 1
	v_add_f32_dpp v67, v68, v68 quad_perm:[2,3,0,1] row_mask:0xf bank_mask:0xf bound_ctrl:1
	v_mov_b32_e32 v68, 0
	s_nop 0
	v_add_f32_dpp v67, v67, v67 row_half_mirror row_mask:0xf bank_mask:0xf bound_ctrl:1
	s_nop 1
	v_mov_b32_dpp v68, v67 row_mirror row_mask:0xf bank_mask:0xf
	s_and_saveexec_b64 s[4:5], vcc
	v_add_f32_e32 v67, v67, v68
	ds_write_b32 v66, v67
	s_or_b64 exec, exec, s[4:5]
	v_mul_f32_e32 v67, v63, v63
	v_mov_b32_e32 v68, v165
	s_nop 1
	v_mov_b32_dpp v68, v67 quad_perm:[1,0,3,2] row_mask:0xf bank_mask:0xf
	v_fmac_f32_e32 v68, v63, v63
	s_nop 1
	v_add_f32_dpp v67, v68, v68 quad_perm:[2,3,0,1] row_mask:0xf bank_mask:0xf bound_ctrl:1
	v_mov_b32_e32 v68, 0
	s_nop 0
	v_add_f32_dpp v67, v67, v67 row_half_mirror row_mask:0xf bank_mask:0xf bound_ctrl:1
	s_nop 1
	v_mov_b32_dpp v68, v67 row_mirror row_mask:0xf bank_mask:0xf
	s_and_saveexec_b64 s[4:5], vcc
	v_add_f32_e32 v67, v67, v68
	ds_write_b32 v66, v67 offset:4
	s_or_b64 exec, exec, s[4:5]
	v_mul_f32_e32 v67, v64, v64
	v_mov_b32_e32 v68, v165
	s_nop 1
	v_mov_b32_dpp v68, v67 quad_perm:[1,0,3,2] row_mask:0xf bank_mask:0xf
	v_fmac_f32_e32 v68, v64, v64
	s_nop 1
	v_add_f32_dpp v67, v68, v68 quad_perm:[2,3,0,1] row_mask:0xf bank_mask:0xf bound_ctrl:1
	v_mov_b32_e32 v68, 0
	s_nop 0
	v_add_f32_dpp v67, v67, v67 row_half_mirror row_mask:0xf bank_mask:0xf bound_ctrl:1
	s_nop 1
	v_mov_b32_dpp v68, v67 row_mirror row_mask:0xf bank_mask:0xf
	s_and_saveexec_b64 s[4:5], vcc
	v_add_f32_e32 v67, v67, v68
	ds_write_b32 v66, v67 offset:8
	s_or_b64 exec, exec, s[4:5]
	v_mul_f32_e32 v67, v65, v65
	v_mov_b32_e32 v68, v165
	s_nop 1
	v_mov_b32_dpp v68, v67 quad_perm:[1,0,3,2] row_mask:0xf bank_mask:0xf
	v_fmac_f32_e32 v68, v65, v65
	s_nop 1
	v_add_f32_dpp v67, v68, v68 quad_perm:[2,3,0,1] row_mask:0xf bank_mask:0xf bound_ctrl:1
	v_mov_b32_e32 v68, 0
	s_nop 0
	v_add_f32_dpp v67, v67, v67 row_half_mirror row_mask:0xf bank_mask:0xf bound_ctrl:1
	s_nop 1
	v_mov_b32_dpp v68, v67 row_mirror row_mask:0xf bank_mask:0xf
	s_and_saveexec_b64 s[4:5], vcc
	v_add_f32_e32 v67, v67, v68
	ds_write_b32 v66, v67 offset:12
	s_or_b64 exec, exec, s[4:5]
	v_mul_f32_e32 v67, v58, v58
	v_mov_b32_e32 v68, v165
	s_nop 1
	v_mov_b32_dpp v68, v67 quad_perm:[1,0,3,2] row_mask:0xf bank_mask:0xf
	v_fmac_f32_e32 v68, v58, v58
	s_nop 1
	v_add_f32_dpp v67, v68, v68 quad_perm:[2,3,0,1] row_mask:0xf bank_mask:0xf bound_ctrl:1
	v_mov_b32_e32 v68, 0
	s_nop 0
	v_add_f32_dpp v67, v67, v67 row_half_mirror row_mask:0xf bank_mask:0xf bound_ctrl:1
	s_nop 1
	v_mov_b32_dpp v68, v67 row_mirror row_mask:0xf bank_mask:0xf
	s_and_saveexec_b64 s[4:5], vcc
	v_add_f32_e32 v67, v67, v68
	ds_write_b32 v66, v67 offset:64
	s_or_b64 exec, exec, s[4:5]
	v_mul_f32_e32 v67, v59, v59
	v_mov_b32_e32 v68, v165
	s_nop 1
	v_mov_b32_dpp v68, v67 quad_perm:[1,0,3,2] row_mask:0xf bank_mask:0xf
	v_fmac_f32_e32 v68, v59, v59
	s_nop 1
	v_add_f32_dpp v67, v68, v68 quad_perm:[2,3,0,1] row_mask:0xf bank_mask:0xf bound_ctrl:1
	v_mov_b32_e32 v68, 0
	s_nop 0
	v_add_f32_dpp v67, v67, v67 row_half_mirror row_mask:0xf bank_mask:0xf bound_ctrl:1
	s_nop 1
	v_mov_b32_dpp v68, v67 row_mirror row_mask:0xf bank_mask:0xf
	s_and_saveexec_b64 s[4:5], vcc
	v_add_f32_e32 v67, v67, v68
	ds_write_b32 v66, v67 offset:68
	s_or_b64 exec, exec, s[4:5]
	v_mul_f32_e32 v67, v60, v60
	v_mov_b32_e32 v68, v165
	s_nop 1
	v_mov_b32_dpp v68, v67 quad_perm:[1,0,3,2] row_mask:0xf bank_mask:0xf
	v_fmac_f32_e32 v68, v60, v60
	s_nop 1
	v_add_f32_dpp v67, v68, v68 quad_perm:[2,3,0,1] row_mask:0xf bank_mask:0xf bound_ctrl:1
	v_mov_b32_e32 v68, 0
	s_nop 0
	v_add_f32_dpp v67, v67, v67 row_half_mirror row_mask:0xf bank_mask:0xf bound_ctrl:1
	s_nop 1
	v_mov_b32_dpp v68, v67 row_mirror row_mask:0xf bank_mask:0xf
	s_and_saveexec_b64 s[4:5], vcc
	v_add_f32_e32 v67, v67, v68
	ds_write_b32 v66, v67 offset:72
	s_or_b64 exec, exec, s[4:5]
	v_mul_f32_e32 v67, v61, v61
	v_mov_b32_e32 v68, v165
	s_nop 1
	v_mov_b32_dpp v68, v67 quad_perm:[1,0,3,2] row_mask:0xf bank_mask:0xf
	v_fmac_f32_e32 v68, v61, v61
	s_nop 1
	v_add_f32_dpp v67, v68, v68 quad_perm:[2,3,0,1] row_mask:0xf bank_mask:0xf bound_ctrl:1
	v_mov_b32_e32 v68, 0
	s_nop 0
	v_add_f32_dpp v67, v67, v67 row_half_mirror row_mask:0xf bank_mask:0xf bound_ctrl:1
	s_nop 1
	v_mov_b32_dpp v68, v67 row_mirror row_mask:0xf bank_mask:0xf
	s_and_saveexec_b64 s[4:5], vcc
	v_add_f32_e32 v67, v67, v68
	ds_write_b32 v66, v67 offset:76
	s_or_b64 exec, exec, s[4:5]
	s_add_i32 s23, s22, 2
	s_cmp_lt_u32 s22, 30
	s_cselect_b64 s[50:51], -1, 0
	s_cmp_gt_u32 s22, 29
	s_cselect_b64 s[48:49], -1, 0
	s_and_b64 vcc, exec, s[48:49]
	v_lshlrev_b32_e32 v119, 1, v164
	s_cbranch_vccnz .LBB0_217
	s_mul_i32 s4, s23, 0xab
	s_bfe_u32 s4, s4, 0x70009
	s_mul_i32 s4, s4, 3
	s_sub_i32 s4, s23, s4
	s_and_b32 s4, s4, 0xff
	s_mul_i32 s4, s4, 0x8c00
	v_add_u32_e32 v66, s4, v76
	v_lshl_add_u32 v67, v106, 1, v66
	v_add3_u32 v66, v66, v77, v119
	s_waitcnt vmcnt(3)
	ds_write_b128 v67, v[22:25]
	s_waitcnt vmcnt(2)
	ds_write_b128 v67, v[26:29] offset:9216
	s_waitcnt vmcnt(1)
	ds_write_b128 v66, v[30:33] offset:18432
	s_waitcnt vmcnt(0)
	ds_write_b128 v66, v[34:37] offset:18448
.LBB0_217:
	v_lshl_add_u32 v81, v83, 2, v143
	s_waitcnt lgkmcnt(0)
	s_barrier
	ds_read_b128 v[170:173], v81
	ds_read_b128 v[174:177], v81 offset:256
	ds_read_b128 v[178:181], v81 offset:512
	ds_read_b128 v[182:185], v81 offset:768
	ds_read_b128 v[186:189], v81 offset:1024
	ds_read_b128 v[190:193], v81 offset:1280
	ds_read_b128 v[194:197], v81 offset:1536
	ds_read_b128 v[198:201], v81 offset:1792
	ds_read_b128 v[212:215], v81 offset:64
	ds_read_b128 v[216:219], v81 offset:320
	ds_read_b128 v[220:223], v81 offset:576
	ds_read_b128 v[224:227], v81 offset:832
	ds_read_b128 v[228:231], v81 offset:1088
	ds_read_b128 v[232:235], v81 offset:1344
	ds_read_b128 v[236:239], v81 offset:1600
	ds_read_b128 v[240:243], v81 offset:1856
	s_waitcnt lgkmcnt(14)
	v_pk_add_f32 v[72:73], v[172:173], v[176:177]
	s_waitcnt lgkmcnt(14)
	v_pk_add_f32 v[70:71], v[170:171], v[174:175]
	s_waitcnt lgkmcnt(13)
	v_pk_add_f32 v[72:73], v[72:73], v[180:181]
	s_waitcnt lgkmcnt(13)
	v_pk_add_f32 v[70:71], v[70:71], v[178:179]
	s_waitcnt lgkmcnt(12)
	v_pk_add_f32 v[72:73], v[72:73], v[184:185]
	s_waitcnt lgkmcnt(12)
	v_pk_add_f32 v[70:71], v[70:71], v[182:183]
	s_waitcnt lgkmcnt(11)
	v_pk_add_f32 v[72:73], v[72:73], v[188:189]
	s_waitcnt lgkmcnt(11)
	v_pk_add_f32 v[70:71], v[70:71], v[186:187]
	s_waitcnt lgkmcnt(10)
	v_pk_add_f32 v[72:73], v[72:73], v[192:193]
	s_waitcnt lgkmcnt(10)
	v_pk_add_f32 v[70:71], v[70:71], v[190:191]
	s_waitcnt lgkmcnt(9)
	v_pk_add_f32 v[72:73], v[72:73], v[196:197]
	s_waitcnt lgkmcnt(9)
	v_pk_add_f32 v[70:71], v[70:71], v[194:195]
	s_waitcnt lgkmcnt(8)
	v_pk_add_f32 v[66:67], v[70:71], v[198:199]
	s_nop 0
	v_fmamk_f32 v66, v66, 0x3c000000, v169
	v_cmp_gt_f32_e32 vcc, s57, v66
	v_mul_f32_e32 v70, 0x4b800000, v66
	s_waitcnt lgkmcnt(8)
	v_pk_add_f32 v[68:69], v[72:73], v[200:201]
	v_cndmask_b32_e32 v66, v66, v70, vcc
	v_rsq_f32_e32 v66, v66
	s_nop 0
	v_mul_f32_e32 v70, 0x45800000, v66
	v_cndmask_b32_e32 v66, v66, v70, vcc
	v_mul_f32_e32 v62, v62, v66
	v_lshlrev_b32_e32 v66, 2, v97
	v_mul_lo_u32 v70, v96, s62
	v_add3_u32 v70, v115, v66, v70
	v_fmamk_f32 v66, v67, 0x3c000000, v169
	v_cmp_gt_f32_e32 vcc, s57, v66
	v_mul_f32_e32 v67, 0x4b800000, v66
	v_lshl_add_u64 v[96:97], s[96:97], 0, v[92:93]
	v_cndmask_b32_e32 v66, v66, v67, vcc
	v_rsq_f32_e32 v66, v66
	s_nop 0
	v_mul_f32_e32 v67, 0x45800000, v66
	v_cndmask_b32_e32 v66, v66, v67, vcc
	v_mul_f32_e32 v63, v63, v66
	ds_write2_b32 v70, v62, v63 offset1:132
	v_fmamk_f32 v62, v68, 0x3c000000, v169
	v_cmp_gt_f32_e32 vcc, s57, v62
	v_mul_f32_e32 v63, 0x4b800000, v62
	s_nop 0
	v_cndmask_b32_e32 v62, v62, v63, vcc
	v_rsq_f32_e32 v62, v62
	s_nop 0
	v_mul_f32_e32 v63, 0x45800000, v62
	v_cndmask_b32_e32 v62, v62, v63, vcc
	v_fmamk_f32 v63, v69, 0x3c000000, v169
	v_mul_f32_e32 v62, v64, v62
	v_cmp_gt_f32_e32 vcc, s57, v63
	v_mul_f32_e32 v64, 0x4b800000, v63
	s_nop 0
	v_cndmask_b32_e32 v63, v63, v64, vcc
	v_rsq_f32_e32 v63, v63
	s_nop 0
	v_mul_f32_e32 v64, 0x45800000, v63
	v_cndmask_b32_e32 v63, v63, v64, vcc
	v_mul_f32_e32 v63, v65, v63
	v_add_u32_e32 v64, 0x400, v70
	ds_write2_b32 v64, v62, v63 offset0:8 offset1:140
	s_waitcnt lgkmcnt(8)
	v_pk_add_f32 v[68:69], v[214:215], v[218:219]
	s_waitcnt lgkmcnt(8)
	v_pk_add_f32 v[66:67], v[212:213], v[216:217]
	s_waitcnt lgkmcnt(7)
	v_pk_add_f32 v[68:69], v[68:69], v[222:223]
	s_waitcnt lgkmcnt(7)
	v_pk_add_f32 v[66:67], v[66:67], v[220:221]
	s_waitcnt lgkmcnt(6)
	v_pk_add_f32 v[68:69], v[68:69], v[226:227]
	s_waitcnt lgkmcnt(6)
	v_pk_add_f32 v[66:67], v[66:67], v[224:225]
	s_waitcnt lgkmcnt(5)
	v_pk_add_f32 v[68:69], v[68:69], v[230:231]
	s_waitcnt lgkmcnt(5)
	v_pk_add_f32 v[66:67], v[66:67], v[228:229]
	s_waitcnt lgkmcnt(4)
	v_pk_add_f32 v[68:69], v[68:69], v[234:235]
	s_waitcnt lgkmcnt(4)
	v_pk_add_f32 v[66:67], v[66:67], v[232:233]
	s_waitcnt lgkmcnt(3)
	v_pk_add_f32 v[68:69], v[68:69], v[238:239]
	s_waitcnt lgkmcnt(3)
	v_pk_add_f32 v[66:67], v[66:67], v[236:237]
	s_waitcnt lgkmcnt(2)
	v_pk_add_f32 v[62:63], v[66:67], v[240:241]
	s_nop 0
	v_fmamk_f32 v62, v62, 0x3c000000, v169
	v_cmp_gt_f32_e32 vcc, s57, v62
	v_mul_f32_e32 v66, 0x4b800000, v62
	s_waitcnt lgkmcnt(2)
	v_pk_add_f32 v[64:65], v[68:69], v[242:243]
	v_cndmask_b32_e32 v62, v62, v66, vcc
	v_rsq_f32_e32 v62, v62
	s_nop 0
	v_mul_f32_e32 v66, 0x45800000, v62
	v_cndmask_b32_e32 v62, v62, v66, vcc
	v_mul_f32_e32 v58, v58, v62
	v_fmamk_f32 v62, v63, 0x3c000000, v169
	v_cmp_gt_f32_e32 vcc, s57, v62
	v_mul_f32_e32 v63, 0x4b800000, v62
	s_nop 0
	v_cndmask_b32_e32 v62, v62, v63, vcc
	v_rsq_f32_e32 v62, v62
	s_nop 0
	v_mul_f32_e32 v63, 0x45800000, v62
	v_cndmask_b32_e32 v62, v62, v63, vcc
	v_mul_f32_e32 v59, v59, v62
	v_add_u32_e32 v62, 0x2000, v70
	ds_write2_b32 v62, v58, v59 offset0:64 offset1:196
	v_fmamk_f32 v58, v64, 0x3c000000, v169
	v_cmp_gt_f32_e32 vcc, s57, v58
	v_mul_f32_e32 v59, 0x4b800000, v58
	s_nop 0
	v_cndmask_b32_e32 v58, v58, v59, vcc
	v_rsq_f32_e32 v58, v58
	s_nop 0
	v_mul_f32_e32 v59, 0x45800000, v58
	v_cndmask_b32_e32 v58, v58, v59, vcc
	v_fmamk_f32 v59, v65, 0x3c000000, v169
	v_mul_f32_e32 v58, v60, v58
	v_cmp_gt_f32_e32 vcc, s57, v59
	v_mul_f32_e32 v60, 0x4b800000, v59
	s_nop 0
	v_cndmask_b32_e32 v59, v59, v60, vcc
	v_rsq_f32_e32 v59, v59
	s_nop 0
	v_mul_f32_e32 v60, 0x45800000, v59
	v_cndmask_b32_e32 v59, v59, v60, vcc
	v_mul_f32_e32 v59, v61, v59
	v_add_u32_e32 v60, 0x2400, v70
	s_andn2_b64 vcc, exec, s[52:53]
	ds_write2_b32 v60, v58, v59 offset0:72 offset1:204
	s_cbranch_vccnz .LBB0_219
	ds_read_b128 v[58:61], v109
	ds_read_b128 v[62:65], v109 offset:16
	s_waitcnt vmcnt(0)
	v_lshlrev_b32_e32 v66, 16, v46
	v_and_b32_e32 v67, 0xffff0000, v46
	s_waitcnt lgkmcnt(1)
	v_pk_mul_f32 v[58:59], v[58:59], v[66:67]
	s_nop 0
	v_cvt_pk_bf16_f32 v46, v58, v59
	v_lshlrev_b32_e32 v58, 16, v47
	v_and_b32_e32 v59, 0xffff0000, v47
	v_pk_mul_f32 v[58:59], v[60:61], v[58:59]
	s_nop 0
	v_cvt_pk_bf16_f32 v47, v58, v59
	v_lshlrev_b32_e32 v58, 16, v48
	v_and_b32_e32 v59, 0xffff0000, v48
	s_waitcnt lgkmcnt(0)
	v_pk_mul_f32 v[58:59], v[62:63], v[58:59]
	s_nop 0
	v_cvt_pk_bf16_f32 v48, v58, v59
	v_lshlrev_b32_e32 v58, 16, v49
	v_and_b32_e32 v59, 0xffff0000, v49
	v_pk_mul_f32 v[58:59], v[64:65], v[58:59]
	s_nop 0
	v_cvt_pk_bf16_f32 v49, v58, v59
	v_add_co_u32_e32 v58, vcc, 0xa170000, v96
	s_nop 1
	v_addc_co_u32_e32 v59, vcc, 0, v97, vcc
	global_store_dwordx4 v[58:59], v[46:49], off

.LBB0_227:
	s_bfe_u32 s4, s37, 0x70009
	s_mul_i32 s4, s4, 3
	s_sub_i32 s4, s36, s4
	s_and_b32 s4, s4, 0xff
	v_ashrrev_i32_e32 v58, 2, v121
	v_lshlrev_b32_e32 v83, 2, v120
	s_mul_i32 s4, s4, 0x8c00
	v_add_u32_e32 v95, v58, v83
	v_lshlrev_b32_e32 v58, 3, v121
	v_add_u32_e32 v62, s4, v168
	v_and_b32_e32 v58, 24, v58
	v_mul_lo_u32 v59, v95, s65
	v_add_u32_e32 v94, v62, v58
	v_add3_u32 v58, v94, v118, v59
	v_lshl_add_u32 v130, v120, 3, v62
	v_add_u32_e32 v62, v145, v108
	ds_read_b64_tr_b16 v[136:137], v58 offset:18432
	ds_read_b64_tr_b16 v[138:139], v58 offset:22784
	ds_read_b64_tr_b16 v[152:153], v58 offset:27136
	ds_read_b64_tr_b16 v[154:155], v58 offset:31488
	ds_read_b128 v[156:159], v62
	v_add_u32_e32 v140, s45, v121
	v_mad_u64_u32 v[160:161], s[4:5], v140, s56, v[130:131]
	ds_read2_b64 v[170:173], v160 offset1:4
	ds_read2_b64 v[174:177], v160 offset0:8 offset1:12
	v_add_u32_e32 v141, v145, v114
	ds_read_b128 v[178:181], v141 offset:1024
	ds_read_b128 v[182:185], v141
	v_add_u32_e32 v142, s43, v121
	v_mad_u64_u32 v[162:163], s[4:5], v142, s56, v[130:131]
	v_mad_u64_u32 v[186:187], s[4:5], v95, s56, v[94:95]
	ds_read2_b64 v[188:191], v162 offset1:4
	ds_read2_b64 v[192:195], v162 offset0:8 offset1:12
	ds_read_b64_tr_b16 v[196:197], v186 offset:9216
	ds_read_b64_tr_b16 v[200:201], v186 offset:9248
	ds_read_b64_tr_b16 v[198:199], v186 offset:11520
	ds_read_b64_tr_b16 v[212:213], v186 offset:13824
	ds_read_b64_tr_b16 v[214:215], v186 offset:16128
	ds_read_b64_tr_b16 v[202:203], v186 offset:11552
	ds_read_b64_tr_b16 v[216:217], v186 offset:13856
	ds_read_b64_tr_b16 v[218:219], v186 offset:16160
	ds_read_b64_tr_b16 v[220:221], v186 offset:9280
	ds_read_b64_tr_b16 v[222:223], v186 offset:11584
	ds_read_b64_tr_b16 v[224:225], v186 offset:13888
	ds_read_b64_tr_b16 v[226:227], v186 offset:16192
	ds_read_b64_tr_b16 v[228:229], v186 offset:9312
	ds_read_b64_tr_b16 v[230:231], v186 offset:11616
	ds_read_b64_tr_b16 v[232:233], v186 offset:13920
	ds_read_b64_tr_b16 v[234:235], v186 offset:16224
	s_waitcnt lgkmcnt(15)
	v_mfma_f32_16x16x32_bf16 v[62:65], v[156:159], v[136:139], v[0:3]
	v_cvt_pk_bf16_f32 v58, v50, v51
	v_cvt_pk_bf16_f32 v59, v52, v53
	v_cvt_pk_bf16_f32 v60, v38, v39
	v_cvt_pk_bf16_f32 v61, v40, v41
	v_cvt_pk_bf16_f32 v98, v42, v43
	v_cvt_pk_bf16_f32 v99, v44, v45
	s_waitcnt lgkmcnt(15)
	v_mfma_f32_16x16x32_bf16 v[62:65], v[170:173], v[58:61], v[62:65]
	v_cvt_pk_bf16_f32 v100, v54, v55
	v_cvt_pk_bf16_f32 v101, v56, v57
	s_waitcnt lgkmcnt(15)
	s_nop 1
	v_mfma_f32_16x16x32_bf16 v[62:65], v[174:177], v[98:101], v[62:65]
	s_waitcnt lgkmcnt(15)
	v_mfma_f32_16x16x32_bf16 v[122:125], v[182:185], v[136:139], v[0:3]
	v_mov_b32_e32 v81, v80
	s_waitcnt lgkmcnt(15)
	v_mfma_f32_16x16x32_bf16 v[122:125], v[178:181], v[152:155], v[122:125]
	v_pk_mul_f32 v[52:53], v[80:81], v[52:53]
	v_pk_mul_f32 v[50:51], v[84:85], v[50:51]
	s_waitcnt lgkmcnt(15)
	v_mfma_f32_16x16x32_bf16 v[58:61], v[188:191], v[58:61], v[122:125]
	s_nop 2
	v_pk_mul_f32 v[40:41], v[80:81], v[40:41]
	v_pk_mul_f32 v[38:39], v[84:85], v[38:39]
	s_waitcnt lgkmcnt(15)
	v_mfma_f32_16x16x32_bf16 v[58:61], v[192:195], v[98:101], v[58:61]
	v_pk_mul_f32 v[44:45], v[80:81], v[44:45]
	v_pk_mul_f32 v[42:43], v[84:85], v[42:43]
	s_waitcnt lgkmcnt(13)
	v_mfma_f32_16x16x32_bf16 v[50:53], v[196:199], v[136:139], v[50:53]
	v_pk_mul_f32 v[56:57], v[80:81], v[56:57]
	s_waitcnt lgkmcnt(11)
	v_mfma_f32_16x16x32_bf16 v[50:53], v[212:215], v[152:155], v[50:53]
	v_pk_mul_f32 v[54:55], v[84:85], v[54:55]
	v_cmp_eq_u32_e32 vcc, 0, v121
	s_waitcnt lgkmcnt(10)
	v_mfma_f32_16x16x32_bf16 v[38:41], v[200:203], v[136:139], v[38:41]
	s_waitcnt lgkmcnt(8)
	v_mfma_f32_16x16x32_bf16 v[38:41], v[216:219], v[152:155], v[38:41]
	s_waitcnt lgkmcnt(6)
	v_mfma_f32_16x16x32_bf16 v[42:45], v[220:223], v[136:139], v[42:45]
	s_waitcnt lgkmcnt(4)
	v_mfma_f32_16x16x32_bf16 v[42:45], v[224:227], v[152:155], v[42:45]
	s_waitcnt lgkmcnt(2)
	v_mfma_f32_16x16x32_bf16 v[54:57], v[228:231], v[136:139], v[54:57]
	s_waitcnt lgkmcnt(0)
	v_mfma_f32_16x16x32_bf16 v[54:57], v[232:235], v[152:155], v[54:57]
	v_mul_f32_e32 v67, v62, v62
	v_mov_b32_e32 v68, v165
	v_add_u32_e32 v66, v83, v112
	v_lshl_add_u32 v66, v66, 2, v147
	v_mov_b32_dpp v68, v67 quad_perm:[1,0,3,2] row_mask:0xf bank_mask:0xf
	v_fmac_f32_e32 v68, v62, v62
	s_nop 1
	v_add_f32_dpp v67, v68, v68 quad_perm:[2,3,0,1] row_mask:0xf bank_mask:0xf bound_ctrl:1
	v_mov_b32_e32 v68, 0
	s_nop 0
	v_add_f32_dpp v67, v67, v67 row_half_mirror row_mask:0xf bank_mask:0xf bound_ctrl:1
	s_nop 1
	v_mov_b32_dpp v68, v67 row_mirror row_mask:0xf bank_mask:0xf
	s_and_saveexec_b64 s[4:5], vcc
	v_add_f32_e32 v67, v67, v68
	ds_write_b32 v66, v67
	s_or_b64 exec, exec, s[4:5]
	v_mul_f32_e32 v67, v63, v63
	v_mov_b32_e32 v68, v165
	s_nop 1
	v_mov_b32_dpp v68, v67 quad_perm:[1,0,3,2] row_mask:0xf bank_mask:0xf
	v_fmac_f32_e32 v68, v63, v63
	s_nop 1
	v_add_f32_dpp v67, v68, v68 quad_perm:[2,3,0,1] row_mask:0xf bank_mask:0xf bound_ctrl:1
	v_mov_b32_e32 v68, 0
	s_nop 0
	v_add_f32_dpp v67, v67, v67 row_half_mirror row_mask:0xf bank_mask:0xf bound_ctrl:1
	s_nop 1
	v_mov_b32_dpp v68, v67 row_mirror row_mask:0xf bank_mask:0xf
	s_and_saveexec_b64 s[4:5], vcc
	v_add_f32_e32 v67, v67, v68
	ds_write_b32 v66, v67 offset:4
	s_or_b64 exec, exec, s[4:5]
	v_mul_f32_e32 v67, v64, v64
	v_mov_b32_e32 v68, v165
	s_nop 1
	v_mov_b32_dpp v68, v67 quad_perm:[1,0,3,2] row_mask:0xf bank_mask:0xf
	v_fmac_f32_e32 v68, v64, v64
	s_nop 1
	v_add_f32_dpp v67, v68, v68 quad_perm:[2,3,0,1] row_mask:0xf bank_mask:0xf bound_ctrl:1
	v_mov_b32_e32 v68, 0
	s_nop 0
	v_add_f32_dpp v67, v67, v67 row_half_mirror row_mask:0xf bank_mask:0xf bound_ctrl:1
	s_nop 1
	v_mov_b32_dpp v68, v67 row_mirror row_mask:0xf bank_mask:0xf
	s_and_saveexec_b64 s[4:5], vcc
	v_add_f32_e32 v67, v67, v68
	ds_write_b32 v66, v67 offset:8
	s_or_b64 exec, exec, s[4:5]
	v_mul_f32_e32 v67, v65, v65
	v_mov_b32_e32 v68, v165
	s_nop 1
	v_mov_b32_dpp v68, v67 quad_perm:[1,0,3,2] row_mask:0xf bank_mask:0xf
	v_fmac_f32_e32 v68, v65, v65
	s_nop 1
	v_add_f32_dpp v67, v68, v68 quad_perm:[2,3,0,1] row_mask:0xf bank_mask:0xf bound_ctrl:1
	v_mov_b32_e32 v68, 0
	s_nop 0
	v_add_f32_dpp v67, v67, v67 row_half_mirror row_mask:0xf bank_mask:0xf bound_ctrl:1
	s_nop 1
	v_mov_b32_dpp v68, v67 row_mirror row_mask:0xf bank_mask:0xf
	s_and_saveexec_b64 s[4:5], vcc
	v_add_f32_e32 v67, v67, v68
	ds_write_b32 v66, v67 offset:12
	s_or_b64 exec, exec, s[4:5]
	v_mul_f32_e32 v67, v58, v58
	v_mov_b32_e32 v68, v165
	s_nop 1
	v_mov_b32_dpp v68, v67 quad_perm:[1,0,3,2] row_mask:0xf bank_mask:0xf
	v_fmac_f32_e32 v68, v58, v58
	s_nop 1
	v_add_f32_dpp v67, v68, v68 quad_perm:[2,3,0,1] row_mask:0xf bank_mask:0xf bound_ctrl:1
	v_mov_b32_e32 v68, 0
	s_nop 0
	v_add_f32_dpp v67, v67, v67 row_half_mirror row_mask:0xf bank_mask:0xf bound_ctrl:1
	s_nop 1
	v_mov_b32_dpp v68, v67 row_mirror row_mask:0xf bank_mask:0xf
	s_and_saveexec_b64 s[4:5], vcc
	v_add_f32_e32 v67, v67, v68
	ds_write_b32 v66, v67 offset:64
	s_or_b64 exec, exec, s[4:5]
	v_mul_f32_e32 v67, v59, v59
	v_mov_b32_e32 v68, v165
	s_nop 1
	v_mov_b32_dpp v68, v67 quad_perm:[1,0,3,2] row_mask:0xf bank_mask:0xf
	v_fmac_f32_e32 v68, v59, v59
	s_nop 1
	v_add_f32_dpp v67, v68, v68 quad_perm:[2,3,0,1] row_mask:0xf bank_mask:0xf bound_ctrl:1
	v_mov_b32_e32 v68, 0
	s_nop 0
	v_add_f32_dpp v67, v67, v67 row_half_mirror row_mask:0xf bank_mask:0xf bound_ctrl:1
	s_nop 1
	v_mov_b32_dpp v68, v67 row_mirror row_mask:0xf bank_mask:0xf
	s_and_saveexec_b64 s[4:5], vcc
	v_add_f32_e32 v67, v67, v68
	ds_write_b32 v66, v67 offset:68
	s_or_b64 exec, exec, s[4:5]
	v_mul_f32_e32 v67, v60, v60
	v_mov_b32_e32 v68, v165
	s_nop 1
	v_mov_b32_dpp v68, v67 quad_perm:[1,0,3,2] row_mask:0xf bank_mask:0xf
	v_fmac_f32_e32 v68, v60, v60
	s_nop 1
	v_add_f32_dpp v67, v68, v68 quad_perm:[2,3,0,1] row_mask:0xf bank_mask:0xf bound_ctrl:1
	v_mov_b32_e32 v68, 0
	s_nop 0
	v_add_f32_dpp v67, v67, v67 row_half_mirror row_mask:0xf bank_mask:0xf bound_ctrl:1
	s_nop 1
	v_mov_b32_dpp v68, v67 row_mirror row_mask:0xf bank_mask:0xf
	s_and_saveexec_b64 s[4:5], vcc
	v_add_f32_e32 v67, v67, v68
	ds_write_b32 v66, v67 offset:72
	s_or_b64 exec, exec, s[4:5]
	v_mul_f32_e32 v67, v61, v61
	v_mov_b32_e32 v68, v165
	s_nop 1
	v_mov_b32_dpp v68, v67 quad_perm:[1,0,3,2] row_mask:0xf bank_mask:0xf
	v_fmac_f32_e32 v68, v61, v61
	s_nop 1
	v_add_f32_dpp v67, v68, v68 quad_perm:[2,3,0,1] row_mask:0xf bank_mask:0xf bound_ctrl:1
	v_mov_b32_e32 v68, 0
	s_nop 0
	v_add_f32_dpp v67, v67, v67 row_half_mirror row_mask:0xf bank_mask:0xf bound_ctrl:1
	s_nop 1
	v_mov_b32_dpp v68, v67 row_mirror row_mask:0xf bank_mask:0xf
	s_and_saveexec_b64 s[4:5], vcc
	v_add_f32_e32 v67, v67, v68
	ds_write_b32 v66, v67 offset:76
	s_or_b64 exec, exec, s[4:5]
	s_andn2_b64 vcc, exec, s[46:47]
	s_cbranch_vccnz .LBB0_190
	s_add_i32 s4, s22, 3
	s_and_b32 s5, s4, 0xff
	s_mulk_i32 s5, 0xab
	s_bfe_u32 s5, s5, 0x70009
	s_mul_i32 s5, s5, 3
	s_sub_i32 s4, s4, s5
	s_and_b32 s4, s4, 0xff
	s_mul_i32 s4, s4, 0x8c00
	v_add_u32_e32 v66, s4, v76
	v_lshl_add_u32 v67, v106, 1, v66
	v_add3_u32 v66, v66, v77, v119
	ds_write_b128 v67, v[6:9]
	ds_write_b128 v67, v[10:13] offset:9216
	ds_write_b128 v66, v[14:17] offset:18432
	ds_write_b128 v66, v[18:21] offset:18448
	s_branch .LBB0_190
